# SwiGLU epilogue (MoE-up + dense-up 128x256 tiles): 8 interleaved element chains, 32-bit offsets with saddr stores, cvt_pk shared by two elements via d16_hi store
# speedup vs baseline: 1.0423x; 1.0076x over previous
.LBB0_896:
	v_or_b32_e32 v128, s34, v185
	v_lshrrev_b32_e32 v129, 3, v181
	v_ashrrev_i32_e32 v128, 1, v128
	v_and_b32_e32 v129, 4, v129
	s_add_i32 s31, s31, s18
	v_or_b32_e32 v128, v128, v183
	v_add3_u32 v130, s31, v189, v129
	v_lshlrev_b32_e32 v128, 1, v128
	v_mad_u32_u24 v128, v130, s88, v128
	s_nop 7
	s_nop 7
	s_nop 3
	v_mul_f32_e32 v131, 0xbfb8aa3b, v112
	v_mul_f32_e32 v132, 0xbfb8aa3b, v113
	v_mul_f32_e32 v133, 0xbfb8aa3b, v114
	v_mul_f32_e32 v134, 0xbfb8aa3b, v115
	v_mul_f32_e32 v135, 0xbfb8aa3b, v116
	v_mul_f32_e32 v136, 0xbfb8aa3b, v117
	v_mul_f32_e32 v137, 0xbfb8aa3b, v118
	v_mul_f32_e32 v138, 0xbfb8aa3b, v119
	v_exp_f32_e32 v131, v131
	v_exp_f32_e32 v132, v132
	v_exp_f32_e32 v133, v133
	v_exp_f32_e32 v134, v134
	v_exp_f32_e32 v135, v135
	v_exp_f32_e32 v136, v136
	v_exp_f32_e32 v137, v137
	v_exp_f32_e32 v138, v138
	v_add_f32_e32 v131, 1.0, v131
	v_add_f32_e32 v132, 1.0, v132
	v_add_f32_e32 v133, 1.0, v133
	v_add_f32_e32 v134, 1.0, v134
	v_add_f32_e32 v135, 1.0, v135
	v_add_f32_e32 v136, 1.0, v136
	v_add_f32_e32 v137, 1.0, v137
	v_add_f32_e32 v138, 1.0, v138
	v_rcp_f32_e32 v131, v131
	v_rcp_f32_e32 v132, v132
	v_rcp_f32_e32 v133, v133
	v_rcp_f32_e32 v134, v134
	v_rcp_f32_e32 v135, v135
	v_rcp_f32_e32 v136, v136
	v_rcp_f32_e32 v137, v137
	v_rcp_f32_e32 v138, v138
	v_mul_f32_e32 v131, v112, v131
	v_mul_f32_e32 v132, v113, v132
	v_mul_f32_e32 v133, v114, v133
	v_mul_f32_e32 v134, v115, v134
	v_mul_f32_e32 v135, v116, v135
	v_mul_f32_e32 v136, v117, v136
	v_mul_f32_e32 v137, v118, v137
	v_mul_f32_e32 v138, v119, v138
	v_mul_f32_e32 v131, v96, v131
	v_mul_f32_e32 v132, v97, v132
	v_mul_f32_e32 v133, v98, v133
	v_mul_f32_e32 v134, v99, v134
	v_mul_f32_e32 v135, v100, v135
	v_mul_f32_e32 v136, v101, v136
	v_mul_f32_e32 v137, v102, v137
	v_mul_f32_e32 v138, v103, v138
	v_add_u32_e32 v112, 0, v128
	v_add_u32_e32 v113, 0x1c00, v128
	v_add_u32_e32 v114, 0x3800, v128
	v_add_u32_e32 v115, 0x5400, v128
	v_add_u32_e32 v116, 0xe000, v128
	v_add_u32_e32 v117, 0xfc00, v128
	v_add_u32_e32 v118, 0x11800, v128
	v_add_u32_e32 v119, 0x13400, v128
	v_cvt_pk_bf16_f32 v139, v131, v132
	v_cvt_pk_bf16_f32 v140, v133, v134
	v_cvt_pk_bf16_f32 v141, v135, v136
	v_cvt_pk_bf16_f32 v142, v137, v138
	global_store_short v112, v139, s[4:5]
	global_store_short_d16_hi v113, v139, s[4:5]
	global_store_short v114, v140, s[4:5]
	global_store_short_d16_hi v115, v140, s[4:5]
	global_store_short v116, v141, s[4:5]
	global_store_short_d16_hi v117, v141, s[4:5]
	global_store_short v118, v142, s[4:5]
	global_store_short_d16_hi v119, v142, s[4:5]
	v_mul_f32_e32 v143, 0xbfb8aa3b, v120
	v_mul_f32_e32 v144, 0xbfb8aa3b, v121
	v_mul_f32_e32 v145, 0xbfb8aa3b, v122
	v_mul_f32_e32 v146, 0xbfb8aa3b, v123
	v_mul_f32_e32 v147, 0xbfb8aa3b, v124
	v_mul_f32_e32 v148, 0xbfb8aa3b, v125
	v_mul_f32_e32 v149, 0xbfb8aa3b, v126
	v_mul_f32_e32 v150, 0xbfb8aa3b, v127
	v_exp_f32_e32 v143, v143
	v_exp_f32_e32 v144, v144
	v_exp_f32_e32 v145, v145
	v_exp_f32_e32 v146, v146
	v_exp_f32_e32 v147, v147
	v_exp_f32_e32 v148, v148
	v_exp_f32_e32 v149, v149
	v_exp_f32_e32 v150, v150
	v_add_f32_e32 v143, 1.0, v143
	v_add_f32_e32 v144, 1.0, v144
	v_add_f32_e32 v145, 1.0, v145
	v_add_f32_e32 v146, 1.0, v146
	v_add_f32_e32 v147, 1.0, v147
	v_add_f32_e32 v148, 1.0, v148
	v_add_f32_e32 v149, 1.0, v149
	v_add_f32_e32 v150, 1.0, v150
	v_rcp_f32_e32 v143, v143
	v_rcp_f32_e32 v144, v144
	v_rcp_f32_e32 v145, v145
	v_rcp_f32_e32 v146, v146
	v_rcp_f32_e32 v147, v147
	v_rcp_f32_e32 v148, v148
	v_rcp_f32_e32 v149, v149
	v_rcp_f32_e32 v150, v150
	v_mul_f32_e32 v143, v120, v143
	v_mul_f32_e32 v144, v121, v144
	v_mul_f32_e32 v145, v122, v145
	v_mul_f32_e32 v146, v123, v146
	v_mul_f32_e32 v147, v124, v147
	v_mul_f32_e32 v148, v125, v148
	v_mul_f32_e32 v149, v126, v149
	v_mul_f32_e32 v150, v127, v150
	v_mul_f32_e32 v143, v104, v143
	v_mul_f32_e32 v144, v105, v144
	v_mul_f32_e32 v145, v106, v145
	v_mul_f32_e32 v146, v107, v146
	v_mul_f32_e32 v147, v108, v147
	v_mul_f32_e32 v148, v109, v148
	v_mul_f32_e32 v149, v110, v149
	v_mul_f32_e32 v150, v111, v150
	v_add_u32_e32 v120, 0x1c000, v128
	v_add_u32_e32 v121, 0x1dc00, v128
	v_add_u32_e32 v122, 0x1f800, v128
	v_add_u32_e32 v123, 0x21400, v128
	v_add_u32_e32 v124, 0x2a000, v128
	v_add_u32_e32 v125, 0x2bc00, v128
	v_add_u32_e32 v126, 0x2d800, v128
	v_add_u32_e32 v127, 0x2f400, v128
	v_cvt_pk_bf16_f32 v151, v143, v144
	v_cvt_pk_bf16_f32 v152, v145, v146
	v_cvt_pk_bf16_f32 v153, v147, v148
	v_cvt_pk_bf16_f32 v154, v149, v150
	global_store_short v120, v151, s[4:5]
	global_store_short_d16_hi v121, v151, s[4:5]
	global_store_short v122, v152, s[4:5]
	global_store_short_d16_hi v123, v152, s[4:5]
	global_store_short v124, v153, s[4:5]
	global_store_short_d16_hi v125, v153, s[4:5]
	global_store_short v126, v154, s[4:5]
	global_store_short_d16_hi v127, v154, s[4:5]
	v_mul_f32_e32 v131, 0xbfb8aa3b, v80
	v_mul_f32_e32 v132, 0xbfb8aa3b, v81
	v_mul_f32_e32 v133, 0xbfb8aa3b, v82
	v_mul_f32_e32 v134, 0xbfb8aa3b, v83
	v_mul_f32_e32 v135, 0xbfb8aa3b, v84
	v_mul_f32_e32 v136, 0xbfb8aa3b, v85
	v_mul_f32_e32 v137, 0xbfb8aa3b, v86
	v_mul_f32_e32 v138, 0xbfb8aa3b, v87
	v_exp_f32_e32 v131, v131
	v_exp_f32_e32 v132, v132
	v_exp_f32_e32 v133, v133
	v_exp_f32_e32 v134, v134
	v_exp_f32_e32 v135, v135
	v_exp_f32_e32 v136, v136
	v_exp_f32_e32 v137, v137
	v_exp_f32_e32 v138, v138
	v_add_f32_e32 v131, 1.0, v131
	v_add_f32_e32 v132, 1.0, v132
	v_add_f32_e32 v133, 1.0, v133
	v_add_f32_e32 v134, 1.0, v134
	v_add_f32_e32 v135, 1.0, v135
	v_add_f32_e32 v136, 1.0, v136
	v_add_f32_e32 v137, 1.0, v137
	v_add_f32_e32 v138, 1.0, v138
	v_rcp_f32_e32 v131, v131
	v_rcp_f32_e32 v132, v132
	v_rcp_f32_e32 v133, v133
	v_rcp_f32_e32 v134, v134
	v_rcp_f32_e32 v135, v135
	v_rcp_f32_e32 v136, v136
	v_rcp_f32_e32 v137, v137
	v_rcp_f32_e32 v138, v138
	v_mul_f32_e32 v131, v80, v131
	v_mul_f32_e32 v132, v81, v132
	v_mul_f32_e32 v133, v82, v133
	v_mul_f32_e32 v134, v83, v134
	v_mul_f32_e32 v135, v84, v135
	v_mul_f32_e32 v136, v85, v136
	v_mul_f32_e32 v137, v86, v137
	v_mul_f32_e32 v138, v87, v138
	v_mul_f32_e32 v131, v64, v131
	v_mul_f32_e32 v132, v65, v132
	v_mul_f32_e32 v133, v66, v133
	v_mul_f32_e32 v134, v67, v134
	v_mul_f32_e32 v135, v68, v135
	v_mul_f32_e32 v136, v69, v136
	v_mul_f32_e32 v137, v70, v137
	v_mul_f32_e32 v138, v71, v138
	v_add_u32_e32 v80, 0x38000, v128
	v_add_u32_e32 v81, 0x39c00, v128
	v_add_u32_e32 v82, 0x3b800, v128
	v_add_u32_e32 v83, 0x3d400, v128
	v_add_u32_e32 v84, 0x46000, v128
	v_add_u32_e32 v85, 0x47c00, v128
	v_add_u32_e32 v86, 0x49800, v128
	v_add_u32_e32 v87, 0x4b400, v128
	v_cvt_pk_bf16_f32 v139, v131, v132
	v_cvt_pk_bf16_f32 v140, v133, v134
	v_cvt_pk_bf16_f32 v141, v135, v136
	v_cvt_pk_bf16_f32 v142, v137, v138
	global_store_short v80, v139, s[4:5]
	global_store_short_d16_hi v81, v139, s[4:5]
	global_store_short v82, v140, s[4:5]
	global_store_short_d16_hi v83, v140, s[4:5]
	global_store_short v84, v141, s[4:5]
	global_store_short_d16_hi v85, v141, s[4:5]
	global_store_short v86, v142, s[4:5]
	global_store_short_d16_hi v87, v142, s[4:5]
	v_mul_f32_e32 v143, 0xbfb8aa3b, v88
	v_mul_f32_e32 v144, 0xbfb8aa3b, v89
	v_mul_f32_e32 v145, 0xbfb8aa3b, v90
	v_mul_f32_e32 v146, 0xbfb8aa3b, v91
	v_mul_f32_e32 v147, 0xbfb8aa3b, v92
	v_mul_f32_e32 v148, 0xbfb8aa3b, v93
	v_mul_f32_e32 v149, 0xbfb8aa3b, v94
	v_mul_f32_e32 v150, 0xbfb8aa3b, v95
	v_exp_f32_e32 v143, v143
	v_exp_f32_e32 v144, v144
	v_exp_f32_e32 v145, v145
	v_exp_f32_e32 v146, v146
	v_exp_f32_e32 v147, v147
	v_exp_f32_e32 v148, v148
	v_exp_f32_e32 v149, v149
	v_exp_f32_e32 v150, v150
	v_add_f32_e32 v143, 1.0, v143
	v_add_f32_e32 v144, 1.0, v144
	v_add_f32_e32 v145, 1.0, v145
	v_add_f32_e32 v146, 1.0, v146
	v_add_f32_e32 v147, 1.0, v147
	v_add_f32_e32 v148, 1.0, v148
	v_add_f32_e32 v149, 1.0, v149
	v_add_f32_e32 v150, 1.0, v150
	v_rcp_f32_e32 v143, v143
	v_rcp_f32_e32 v144, v144
	v_rcp_f32_e32 v145, v145
	v_rcp_f32_e32 v146, v146
	v_rcp_f32_e32 v147, v147
	v_rcp_f32_e32 v148, v148
	v_rcp_f32_e32 v149, v149
	v_rcp_f32_e32 v150, v150
	v_mul_f32_e32 v143, v88, v143
	v_mul_f32_e32 v144, v89, v144
	v_mul_f32_e32 v145, v90, v145
	v_mul_f32_e32 v146, v91, v146
	v_mul_f32_e32 v147, v92, v147
	v_mul_f32_e32 v148, v93, v148
	v_mul_f32_e32 v149, v94, v149
	v_mul_f32_e32 v150, v95, v150
	v_mul_f32_e32 v143, v72, v143
	v_mul_f32_e32 v144, v73, v144
	v_mul_f32_e32 v145, v74, v145
	v_mul_f32_e32 v146, v75, v146
	v_mul_f32_e32 v147, v76, v147
	v_mul_f32_e32 v148, v77, v148
	v_mul_f32_e32 v149, v78, v149
	v_mul_f32_e32 v150, v79, v150
	v_add_u32_e32 v88, 0x54000, v128
	v_add_u32_e32 v89, 0x55c00, v128
	v_add_u32_e32 v90, 0x57800, v128
	v_add_u32_e32 v91, 0x59400, v128
	v_add_u32_e32 v92, 0x62000, v128
	v_add_u32_e32 v93, 0x63c00, v128
	v_add_u32_e32 v94, 0x65800, v128
	v_add_u32_e32 v95, 0x67400, v128
	v_cvt_pk_bf16_f32 v151, v143, v144
	v_cvt_pk_bf16_f32 v152, v145, v146
	v_cvt_pk_bf16_f32 v153, v147, v148
	v_cvt_pk_bf16_f32 v154, v149, v150
	global_store_short v88, v151, s[4:5]
	global_store_short_d16_hi v89, v151, s[4:5]
	global_store_short v90, v152, s[4:5]
	global_store_short_d16_hi v91, v152, s[4:5]
	global_store_short v92, v153, s[4:5]
	global_store_short_d16_hi v93, v153, s[4:5]
	global_store_short v94, v154, s[4:5]
	global_store_short_d16_hi v95, v154, s[4:5]
	v_mul_f32_e32 v131, 0xbfb8aa3b, v48
	v_mul_f32_e32 v132, 0xbfb8aa3b, v49
	v_mul_f32_e32 v133, 0xbfb8aa3b, v50
	v_mul_f32_e32 v134, 0xbfb8aa3b, v51
	v_mul_f32_e32 v135, 0xbfb8aa3b, v52
	v_mul_f32_e32 v136, 0xbfb8aa3b, v53
	v_mul_f32_e32 v137, 0xbfb8aa3b, v54
	v_mul_f32_e32 v138, 0xbfb8aa3b, v55
	v_exp_f32_e32 v131, v131
	v_exp_f32_e32 v132, v132
	v_exp_f32_e32 v133, v133
	v_exp_f32_e32 v134, v134
	v_exp_f32_e32 v135, v135
	v_exp_f32_e32 v136, v136
	v_exp_f32_e32 v137, v137
	v_exp_f32_e32 v138, v138
	v_add_f32_e32 v131, 1.0, v131
	v_add_f32_e32 v132, 1.0, v132
	v_add_f32_e32 v133, 1.0, v133
	v_add_f32_e32 v134, 1.0, v134
	v_add_f32_e32 v135, 1.0, v135
	v_add_f32_e32 v136, 1.0, v136
	v_add_f32_e32 v137, 1.0, v137
	v_add_f32_e32 v138, 1.0, v138
	v_rcp_f32_e32 v131, v131
	v_rcp_f32_e32 v132, v132
	v_rcp_f32_e32 v133, v133
	v_rcp_f32_e32 v134, v134
	v_rcp_f32_e32 v135, v135
	v_rcp_f32_e32 v136, v136
	v_rcp_f32_e32 v137, v137
	v_rcp_f32_e32 v138, v138
	v_mul_f32_e32 v131, v48, v131
	v_mul_f32_e32 v132, v49, v132
	v_mul_f32_e32 v133, v50, v133
	v_mul_f32_e32 v134, v51, v134
	v_mul_f32_e32 v135, v52, v135
	v_mul_f32_e32 v136, v53, v136
	v_mul_f32_e32 v137, v54, v137
	v_mul_f32_e32 v138, v55, v138
	v_mul_f32_e32 v131, v32, v131
	v_mul_f32_e32 v132, v33, v132
	v_mul_f32_e32 v133, v34, v133
	v_mul_f32_e32 v134, v35, v134
	v_mul_f32_e32 v135, v36, v135
	v_mul_f32_e32 v136, v37, v136
	v_mul_f32_e32 v137, v38, v137
	v_mul_f32_e32 v138, v39, v138
	v_add_u32_e32 v48, 64, v128
	v_add_u32_e32 v49, 0x1c40, v128
	v_add_u32_e32 v50, 0x3840, v128
	v_add_u32_e32 v51, 0x5440, v128
	v_add_u32_e32 v52, 0xe040, v128
	v_add_u32_e32 v53, 0xfc40, v128
	v_add_u32_e32 v54, 0x11840, v128
	v_add_u32_e32 v55, 0x13440, v128
	v_cvt_pk_bf16_f32 v139, v131, v132
	v_cvt_pk_bf16_f32 v140, v133, v134
	v_cvt_pk_bf16_f32 v141, v135, v136
	v_cvt_pk_bf16_f32 v142, v137, v138
	global_store_short v48, v139, s[4:5]
	global_store_short_d16_hi v49, v139, s[4:5]
	global_store_short v50, v140, s[4:5]
	global_store_short_d16_hi v51, v140, s[4:5]
	global_store_short v52, v141, s[4:5]
	global_store_short_d16_hi v53, v141, s[4:5]
	global_store_short v54, v142, s[4:5]
	global_store_short_d16_hi v55, v142, s[4:5]
	v_mul_f32_e32 v143, 0xbfb8aa3b, v56
	v_mul_f32_e32 v144, 0xbfb8aa3b, v57
	v_mul_f32_e32 v145, 0xbfb8aa3b, v58
	v_mul_f32_e32 v146, 0xbfb8aa3b, v59
	v_mul_f32_e32 v147, 0xbfb8aa3b, v60
	v_mul_f32_e32 v148, 0xbfb8aa3b, v61
	v_mul_f32_e32 v149, 0xbfb8aa3b, v62
	v_mul_f32_e32 v150, 0xbfb8aa3b, v63
	v_exp_f32_e32 v143, v143
	v_exp_f32_e32 v144, v144
	v_exp_f32_e32 v145, v145
	v_exp_f32_e32 v146, v146
	v_exp_f32_e32 v147, v147
	v_exp_f32_e32 v148, v148
	v_exp_f32_e32 v149, v149
	v_exp_f32_e32 v150, v150
	v_add_f32_e32 v143, 1.0, v143
	v_add_f32_e32 v144, 1.0, v144
	v_add_f32_e32 v145, 1.0, v145
	v_add_f32_e32 v146, 1.0, v146
	v_add_f32_e32 v147, 1.0, v147
	v_add_f32_e32 v148, 1.0, v148
	v_add_f32_e32 v149, 1.0, v149
	v_add_f32_e32 v150, 1.0, v150
	v_rcp_f32_e32 v143, v143
	v_rcp_f32_e32 v144, v144
	v_rcp_f32_e32 v145, v145
	v_rcp_f32_e32 v146, v146
	v_rcp_f32_e32 v147, v147
	v_rcp_f32_e32 v148, v148
	v_rcp_f32_e32 v149, v149
	v_rcp_f32_e32 v150, v150
	v_mul_f32_e32 v143, v56, v143
	v_mul_f32_e32 v144, v57, v144
	v_mul_f32_e32 v145, v58, v145
	v_mul_f32_e32 v146, v59, v146
	v_mul_f32_e32 v147, v60, v147
	v_mul_f32_e32 v148, v61, v148
	v_mul_f32_e32 v149, v62, v149
	v_mul_f32_e32 v150, v63, v150
	v_mul_f32_e32 v143, v40, v143
	v_mul_f32_e32 v144, v41, v144
	v_mul_f32_e32 v145, v42, v145
	v_mul_f32_e32 v146, v43, v146
	v_mul_f32_e32 v147, v44, v147
	v_mul_f32_e32 v148, v45, v148
	v_mul_f32_e32 v149, v46, v149
	v_mul_f32_e32 v150, v47, v150
	v_add_u32_e32 v56, 0x1c040, v128
	v_add_u32_e32 v57, 0x1dc40, v128
	v_add_u32_e32 v58, 0x1f840, v128
	v_add_u32_e32 v59, 0x21440, v128
	v_add_u32_e32 v60, 0x2a040, v128
	v_add_u32_e32 v61, 0x2bc40, v128
	v_add_u32_e32 v62, 0x2d840, v128
	v_add_u32_e32 v63, 0x2f440, v128
	v_cvt_pk_bf16_f32 v151, v143, v144
	v_cvt_pk_bf16_f32 v152, v145, v146
	v_cvt_pk_bf16_f32 v153, v147, v148
	v_cvt_pk_bf16_f32 v154, v149, v150
	global_store_short v56, v151, s[4:5]
	global_store_short_d16_hi v57, v151, s[4:5]
	global_store_short v58, v152, s[4:5]
	global_store_short_d16_hi v59, v152, s[4:5]
	global_store_short v60, v153, s[4:5]
	global_store_short_d16_hi v61, v153, s[4:5]
	global_store_short v62, v154, s[4:5]
	global_store_short_d16_hi v63, v154, s[4:5]
	v_mul_f32_e32 v131, 0xbfb8aa3b, v16
	v_mul_f32_e32 v132, 0xbfb8aa3b, v17
	v_mul_f32_e32 v133, 0xbfb8aa3b, v18
	v_mul_f32_e32 v134, 0xbfb8aa3b, v19
	v_mul_f32_e32 v135, 0xbfb8aa3b, v20
	v_mul_f32_e32 v136, 0xbfb8aa3b, v21
	v_mul_f32_e32 v137, 0xbfb8aa3b, v22
	v_mul_f32_e32 v138, 0xbfb8aa3b, v23
	v_exp_f32_e32 v131, v131
	v_exp_f32_e32 v132, v132
	v_exp_f32_e32 v133, v133
	v_exp_f32_e32 v134, v134
	v_exp_f32_e32 v135, v135
	v_exp_f32_e32 v136, v136
	v_exp_f32_e32 v137, v137
	v_exp_f32_e32 v138, v138
	v_add_f32_e32 v131, 1.0, v131
	v_add_f32_e32 v132, 1.0, v132
	v_add_f32_e32 v133, 1.0, v133
	v_add_f32_e32 v134, 1.0, v134
	v_add_f32_e32 v135, 1.0, v135
	v_add_f32_e32 v136, 1.0, v136
	v_add_f32_e32 v137, 1.0, v137
	v_add_f32_e32 v138, 1.0, v138
	v_rcp_f32_e32 v131, v131
	v_rcp_f32_e32 v132, v132
	v_rcp_f32_e32 v133, v133
	v_rcp_f32_e32 v134, v134
	v_rcp_f32_e32 v135, v135
	v_rcp_f32_e32 v136, v136
	v_rcp_f32_e32 v137, v137
	v_rcp_f32_e32 v138, v138
	v_mul_f32_e32 v131, v16, v131
	v_mul_f32_e32 v132, v17, v132
	v_mul_f32_e32 v133, v18, v133
	v_mul_f32_e32 v134, v19, v134
	v_mul_f32_e32 v135, v20, v135
	v_mul_f32_e32 v136, v21, v136
	v_mul_f32_e32 v137, v22, v137
	v_mul_f32_e32 v138, v23, v138
	v_mul_f32_e32 v131, v0, v131
	v_mul_f32_e32 v132, v1, v132
	v_mul_f32_e32 v133, v2, v133
	v_mul_f32_e32 v134, v3, v134
	v_mul_f32_e32 v135, v4, v135
	v_mul_f32_e32 v136, v5, v136
	v_mul_f32_e32 v137, v6, v137
	v_mul_f32_e32 v138, v7, v138
	v_add_u32_e32 v16, 0x38040, v128
	v_add_u32_e32 v17, 0x39c40, v128
	v_add_u32_e32 v18, 0x3b840, v128
	v_add_u32_e32 v19, 0x3d440, v128
	v_add_u32_e32 v20, 0x46040, v128
	v_add_u32_e32 v21, 0x47c40, v128
	v_add_u32_e32 v22, 0x49840, v128
	v_add_u32_e32 v23, 0x4b440, v128
	v_cvt_pk_bf16_f32 v139, v131, v132
	v_cvt_pk_bf16_f32 v140, v133, v134
	v_cvt_pk_bf16_f32 v141, v135, v136
	v_cvt_pk_bf16_f32 v142, v137, v138
	global_store_short v16, v139, s[4:5]
	global_store_short_d16_hi v17, v139, s[4:5]
	global_store_short v18, v140, s[4:5]
	global_store_short_d16_hi v19, v140, s[4:5]
	global_store_short v20, v141, s[4:5]
	global_store_short_d16_hi v21, v141, s[4:5]
	global_store_short v22, v142, s[4:5]
	global_store_short_d16_hi v23, v142, s[4:5]
	v_mul_f32_e32 v143, 0xbfb8aa3b, v24
	v_mul_f32_e32 v144, 0xbfb8aa3b, v25
	v_mul_f32_e32 v145, 0xbfb8aa3b, v26
	v_mul_f32_e32 v146, 0xbfb8aa3b, v27
	v_mul_f32_e32 v147, 0xbfb8aa3b, v28
	v_mul_f32_e32 v148, 0xbfb8aa3b, v29
	v_mul_f32_e32 v149, 0xbfb8aa3b, v30
	v_mul_f32_e32 v150, 0xbfb8aa3b, v31
	v_exp_f32_e32 v143, v143
	v_exp_f32_e32 v144, v144
	v_exp_f32_e32 v145, v145
	v_exp_f32_e32 v146, v146
	v_exp_f32_e32 v147, v147
	v_exp_f32_e32 v148, v148
	v_exp_f32_e32 v149, v149
	v_exp_f32_e32 v150, v150
	v_add_f32_e32 v143, 1.0, v143
	v_add_f32_e32 v144, 1.0, v144
	v_add_f32_e32 v145, 1.0, v145
	v_add_f32_e32 v146, 1.0, v146
	v_add_f32_e32 v147, 1.0, v147
	v_add_f32_e32 v148, 1.0, v148
	v_add_f32_e32 v149, 1.0, v149
	v_add_f32_e32 v150, 1.0, v150
	v_rcp_f32_e32 v143, v143
	v_rcp_f32_e32 v144, v144
	v_rcp_f32_e32 v145, v145
	v_rcp_f32_e32 v146, v146
	v_rcp_f32_e32 v147, v147
	v_rcp_f32_e32 v148, v148
	v_rcp_f32_e32 v149, v149
	v_rcp_f32_e32 v150, v150
	v_mul_f32_e32 v143, v24, v143
	v_mul_f32_e32 v144, v25, v144
	v_mul_f32_e32 v145, v26, v145
	v_mul_f32_e32 v146, v27, v146
	v_mul_f32_e32 v147, v28, v147
	v_mul_f32_e32 v148, v29, v148
	v_mul_f32_e32 v149, v30, v149
	v_mul_f32_e32 v150, v31, v150
	v_mul_f32_e32 v143, v8, v143
	v_mul_f32_e32 v144, v9, v144
	v_mul_f32_e32 v145, v10, v145
	v_mul_f32_e32 v146, v11, v146
	v_mul_f32_e32 v147, v12, v147
	v_mul_f32_e32 v148, v13, v148
	v_mul_f32_e32 v149, v14, v149
	v_mul_f32_e32 v150, v15, v150
	v_add_u32_e32 v24, 0x54040, v128
	v_add_u32_e32 v25, 0x55c40, v128
	v_add_u32_e32 v26, 0x57840, v128
	v_add_u32_e32 v27, 0x59440, v128
	v_add_u32_e32 v28, 0x62040, v128
	v_add_u32_e32 v29, 0x63c40, v128
	v_add_u32_e32 v30, 0x65840, v128
	v_add_u32_e32 v31, 0x67440, v128
	v_cvt_pk_bf16_f32 v151, v143, v144
	v_cvt_pk_bf16_f32 v152, v145, v146
	v_cvt_pk_bf16_f32 v153, v147, v148
	v_cvt_pk_bf16_f32 v154, v149, v150
	global_store_short v24, v151, s[4:5]
	global_store_short_d16_hi v25, v151, s[4:5]
	global_store_short v26, v152, s[4:5]
	global_store_short_d16_hi v27, v152, s[4:5]
	global_store_short v28, v153, s[4:5]
	global_store_short_d16_hi v29, v153, s[4:5]
	global_store_short v30, v154, s[4:5]
	global_store_short_d16_hi v31, v154, s[4:5]
	s_add_i32 s30, s30, s85
	s_cmp_ge_i32 s30, s20
	s_cbranch_scc1 .LBB0_905

.LBB0_992:
	v_add_u32_e32 v128, s13, v187
	v_or_b32_e32 v129, s14, v181
	v_lshrrev_b32_e32 v130, 3, v178
	v_and_or_b32 v130, v130, 4, v128
	v_ashrrev_i32_e32 v128, 1, v129
	v_or_b32_e32 v128, v128, v185
	v_lshlrev_b32_e32 v128, 1, v128
	v_mad_u32_u24 v128, v130, s90, v128
	s_nop 7
	s_nop 7
	s_nop 3
	v_mul_f32_e32 v131, 0xbfb8aa3b, v112
	v_mul_f32_e32 v132, 0xbfb8aa3b, v113
	v_mul_f32_e32 v133, 0xbfb8aa3b, v114
	v_mul_f32_e32 v134, 0xbfb8aa3b, v115
	v_mul_f32_e32 v135, 0xbfb8aa3b, v116
	v_mul_f32_e32 v136, 0xbfb8aa3b, v117
	v_mul_f32_e32 v137, 0xbfb8aa3b, v118
	v_mul_f32_e32 v138, 0xbfb8aa3b, v119
	v_exp_f32_e32 v131, v131
	v_exp_f32_e32 v132, v132
	v_exp_f32_e32 v133, v133
	v_exp_f32_e32 v134, v134
	v_exp_f32_e32 v135, v135
	v_exp_f32_e32 v136, v136
	v_exp_f32_e32 v137, v137
	v_exp_f32_e32 v138, v138
	v_add_f32_e32 v131, 1.0, v131
	v_add_f32_e32 v132, 1.0, v132
	v_add_f32_e32 v133, 1.0, v133
	v_add_f32_e32 v134, 1.0, v134
	v_add_f32_e32 v135, 1.0, v135
	v_add_f32_e32 v136, 1.0, v136
	v_add_f32_e32 v137, 1.0, v137
	v_add_f32_e32 v138, 1.0, v138
	v_rcp_f32_e32 v131, v131
	v_rcp_f32_e32 v132, v132
	v_rcp_f32_e32 v133, v133
	v_rcp_f32_e32 v134, v134
	v_rcp_f32_e32 v135, v135
	v_rcp_f32_e32 v136, v136
	v_rcp_f32_e32 v137, v137
	v_rcp_f32_e32 v138, v138
	v_mul_f32_e32 v131, v112, v131
	v_mul_f32_e32 v132, v113, v132
	v_mul_f32_e32 v133, v114, v133
	v_mul_f32_e32 v134, v115, v134
	v_mul_f32_e32 v135, v116, v135
	v_mul_f32_e32 v136, v117, v136
	v_mul_f32_e32 v137, v118, v137
	v_mul_f32_e32 v138, v119, v138
	v_mul_f32_e32 v131, v96, v131
	v_mul_f32_e32 v132, v97, v132
	v_mul_f32_e32 v133, v98, v133
	v_mul_f32_e32 v134, v99, v134
	v_mul_f32_e32 v135, v100, v135
	v_mul_f32_e32 v136, v101, v136
	v_mul_f32_e32 v137, v102, v137
	v_mul_f32_e32 v138, v103, v138
	v_add_u32_e32 v112, 0, v128
	v_add_u32_e32 v113, 0x1600, v128
	v_add_u32_e32 v114, 0x2c00, v128
	v_add_u32_e32 v115, 0x4200, v128
	v_add_u32_e32 v116, 0xb000, v128
	v_add_u32_e32 v117, 0xc600, v128
	v_add_u32_e32 v118, 0xdc00, v128
	v_add_u32_e32 v119, 0xf200, v128
	v_cvt_pk_bf16_f32 v139, v131, v132
	v_cvt_pk_bf16_f32 v140, v133, v134
	v_cvt_pk_bf16_f32 v141, v135, v136
	v_cvt_pk_bf16_f32 v142, v137, v138
	global_store_short v112, v139, s[0:1]
	global_store_short_d16_hi v113, v139, s[0:1]
	global_store_short v114, v140, s[0:1]
	global_store_short_d16_hi v115, v140, s[0:1]
	global_store_short v116, v141, s[0:1]
	global_store_short_d16_hi v117, v141, s[0:1]
	global_store_short v118, v142, s[0:1]
	global_store_short_d16_hi v119, v142, s[0:1]
	v_mul_f32_e32 v143, 0xbfb8aa3b, v120
	v_mul_f32_e32 v144, 0xbfb8aa3b, v121
	v_mul_f32_e32 v145, 0xbfb8aa3b, v122
	v_mul_f32_e32 v146, 0xbfb8aa3b, v123
	v_mul_f32_e32 v147, 0xbfb8aa3b, v124
	v_mul_f32_e32 v148, 0xbfb8aa3b, v125
	v_mul_f32_e32 v149, 0xbfb8aa3b, v126
	v_mul_f32_e32 v150, 0xbfb8aa3b, v127
	v_exp_f32_e32 v143, v143
	v_exp_f32_e32 v144, v144
	v_exp_f32_e32 v145, v145
	v_exp_f32_e32 v146, v146
	v_exp_f32_e32 v147, v147
	v_exp_f32_e32 v148, v148
	v_exp_f32_e32 v149, v149
	v_exp_f32_e32 v150, v150
	v_add_f32_e32 v143, 1.0, v143
	v_add_f32_e32 v144, 1.0, v144
	v_add_f32_e32 v145, 1.0, v145
	v_add_f32_e32 v146, 1.0, v146
	v_add_f32_e32 v147, 1.0, v147
	v_add_f32_e32 v148, 1.0, v148
	v_add_f32_e32 v149, 1.0, v149
	v_add_f32_e32 v150, 1.0, v150
	v_rcp_f32_e32 v143, v143
	v_rcp_f32_e32 v144, v144
	v_rcp_f32_e32 v145, v145
	v_rcp_f32_e32 v146, v146
	v_rcp_f32_e32 v147, v147
	v_rcp_f32_e32 v148, v148
	v_rcp_f32_e32 v149, v149
	v_rcp_f32_e32 v150, v150
	v_mul_f32_e32 v143, v120, v143
	v_mul_f32_e32 v144, v121, v144
	v_mul_f32_e32 v145, v122, v145
	v_mul_f32_e32 v146, v123, v146
	v_mul_f32_e32 v147, v124, v147
	v_mul_f32_e32 v148, v125, v148
	v_mul_f32_e32 v149, v126, v149
	v_mul_f32_e32 v150, v127, v150
	v_mul_f32_e32 v143, v104, v143
	v_mul_f32_e32 v144, v105, v144
	v_mul_f32_e32 v145, v106, v145
	v_mul_f32_e32 v146, v107, v146
	v_mul_f32_e32 v147, v108, v147
	v_mul_f32_e32 v148, v109, v148
	v_mul_f32_e32 v149, v110, v149
	v_mul_f32_e32 v150, v111, v150
	v_add_u32_e32 v120, 0x16000, v128
	v_add_u32_e32 v121, 0x17600, v128
	v_add_u32_e32 v122, 0x18c00, v128
	v_add_u32_e32 v123, 0x1a200, v128
	v_add_u32_e32 v124, 0x21000, v128
	v_add_u32_e32 v125, 0x22600, v128
	v_add_u32_e32 v126, 0x23c00, v128
	v_add_u32_e32 v127, 0x25200, v128
	v_cvt_pk_bf16_f32 v151, v143, v144
	v_cvt_pk_bf16_f32 v152, v145, v146
	v_cvt_pk_bf16_f32 v153, v147, v148
	v_cvt_pk_bf16_f32 v154, v149, v150
	global_store_short v120, v151, s[0:1]
	global_store_short_d16_hi v121, v151, s[0:1]
	global_store_short v122, v152, s[0:1]
	global_store_short_d16_hi v123, v152, s[0:1]
	global_store_short v124, v153, s[0:1]
	global_store_short_d16_hi v125, v153, s[0:1]
	global_store_short v126, v154, s[0:1]
	global_store_short_d16_hi v127, v154, s[0:1]
	v_mul_f32_e32 v131, 0xbfb8aa3b, v80
	v_mul_f32_e32 v132, 0xbfb8aa3b, v81
	v_mul_f32_e32 v133, 0xbfb8aa3b, v82
	v_mul_f32_e32 v134, 0xbfb8aa3b, v83
	v_mul_f32_e32 v135, 0xbfb8aa3b, v84
	v_mul_f32_e32 v136, 0xbfb8aa3b, v85
	v_mul_f32_e32 v137, 0xbfb8aa3b, v86
	v_mul_f32_e32 v138, 0xbfb8aa3b, v87
	v_exp_f32_e32 v131, v131
	v_exp_f32_e32 v132, v132
	v_exp_f32_e32 v133, v133
	v_exp_f32_e32 v134, v134
	v_exp_f32_e32 v135, v135
	v_exp_f32_e32 v136, v136
	v_exp_f32_e32 v137, v137
	v_exp_f32_e32 v138, v138
	v_add_f32_e32 v131, 1.0, v131
	v_add_f32_e32 v132, 1.0, v132
	v_add_f32_e32 v133, 1.0, v133
	v_add_f32_e32 v134, 1.0, v134
	v_add_f32_e32 v135, 1.0, v135
	v_add_f32_e32 v136, 1.0, v136
	v_add_f32_e32 v137, 1.0, v137
	v_add_f32_e32 v138, 1.0, v138
	v_rcp_f32_e32 v131, v131
	v_rcp_f32_e32 v132, v132
	v_rcp_f32_e32 v133, v133
	v_rcp_f32_e32 v134, v134
	v_rcp_f32_e32 v135, v135
	v_rcp_f32_e32 v136, v136
	v_rcp_f32_e32 v137, v137
	v_rcp_f32_e32 v138, v138
	v_mul_f32_e32 v131, v80, v131
	v_mul_f32_e32 v132, v81, v132
	v_mul_f32_e32 v133, v82, v133
	v_mul_f32_e32 v134, v83, v134
	v_mul_f32_e32 v135, v84, v135
	v_mul_f32_e32 v136, v85, v136
	v_mul_f32_e32 v137, v86, v137
	v_mul_f32_e32 v138, v87, v138
	v_mul_f32_e32 v131, v64, v131
	v_mul_f32_e32 v132, v65, v132
	v_mul_f32_e32 v133, v66, v133
	v_mul_f32_e32 v134, v67, v134
	v_mul_f32_e32 v135, v68, v135
	v_mul_f32_e32 v136, v69, v136
	v_mul_f32_e32 v137, v70, v137
	v_mul_f32_e32 v138, v71, v138
	v_add_u32_e32 v80, 0x2c000, v128
	v_add_u32_e32 v81, 0x2d600, v128
	v_add_u32_e32 v82, 0x2ec00, v128
	v_add_u32_e32 v83, 0x30200, v128
	v_add_u32_e32 v84, 0x37000, v128
	v_add_u32_e32 v85, 0x38600, v128
	v_add_u32_e32 v86, 0x39c00, v128
	v_add_u32_e32 v87, 0x3b200, v128
	v_cvt_pk_bf16_f32 v139, v131, v132
	v_cvt_pk_bf16_f32 v140, v133, v134
	v_cvt_pk_bf16_f32 v141, v135, v136
	v_cvt_pk_bf16_f32 v142, v137, v138
	global_store_short v80, v139, s[0:1]
	global_store_short_d16_hi v81, v139, s[0:1]
	global_store_short v82, v140, s[0:1]
	global_store_short_d16_hi v83, v140, s[0:1]
	global_store_short v84, v141, s[0:1]
	global_store_short_d16_hi v85, v141, s[0:1]
	global_store_short v86, v142, s[0:1]
	global_store_short_d16_hi v87, v142, s[0:1]
	v_mul_f32_e32 v143, 0xbfb8aa3b, v88
	v_mul_f32_e32 v144, 0xbfb8aa3b, v89
	v_mul_f32_e32 v145, 0xbfb8aa3b, v90
	v_mul_f32_e32 v146, 0xbfb8aa3b, v91
	v_mul_f32_e32 v147, 0xbfb8aa3b, v92
	v_mul_f32_e32 v148, 0xbfb8aa3b, v93
	v_mul_f32_e32 v149, 0xbfb8aa3b, v94
	v_mul_f32_e32 v150, 0xbfb8aa3b, v95
	v_exp_f32_e32 v143, v143
	v_exp_f32_e32 v144, v144
	v_exp_f32_e32 v145, v145
	v_exp_f32_e32 v146, v146
	v_exp_f32_e32 v147, v147
	v_exp_f32_e32 v148, v148
	v_exp_f32_e32 v149, v149
	v_exp_f32_e32 v150, v150
	v_add_f32_e32 v143, 1.0, v143
	v_add_f32_e32 v144, 1.0, v144
	v_add_f32_e32 v145, 1.0, v145
	v_add_f32_e32 v146, 1.0, v146
	v_add_f32_e32 v147, 1.0, v147
	v_add_f32_e32 v148, 1.0, v148
	v_add_f32_e32 v149, 1.0, v149
	v_add_f32_e32 v150, 1.0, v150
	v_rcp_f32_e32 v143, v143
	v_rcp_f32_e32 v144, v144
	v_rcp_f32_e32 v145, v145
	v_rcp_f32_e32 v146, v146
	v_rcp_f32_e32 v147, v147
	v_rcp_f32_e32 v148, v148
	v_rcp_f32_e32 v149, v149
	v_rcp_f32_e32 v150, v150
	v_mul_f32_e32 v143, v88, v143
	v_mul_f32_e32 v144, v89, v144
	v_mul_f32_e32 v145, v90, v145
	v_mul_f32_e32 v146, v91, v146
	v_mul_f32_e32 v147, v92, v147
	v_mul_f32_e32 v148, v93, v148
	v_mul_f32_e32 v149, v94, v149
	v_mul_f32_e32 v150, v95, v150
	v_mul_f32_e32 v143, v72, v143
	v_mul_f32_e32 v144, v73, v144
	v_mul_f32_e32 v145, v74, v145
	v_mul_f32_e32 v146, v75, v146
	v_mul_f32_e32 v147, v76, v147
	v_mul_f32_e32 v148, v77, v148
	v_mul_f32_e32 v149, v78, v149
	v_mul_f32_e32 v150, v79, v150
	v_add_u32_e32 v88, 0x42000, v128
	v_add_u32_e32 v89, 0x43600, v128
	v_add_u32_e32 v90, 0x44c00, v128
	v_add_u32_e32 v91, 0x46200, v128
	v_add_u32_e32 v92, 0x4d000, v128
	v_add_u32_e32 v93, 0x4e600, v128
	v_add_u32_e32 v94, 0x4fc00, v128
	v_add_u32_e32 v95, 0x51200, v128
	v_cvt_pk_bf16_f32 v151, v143, v144
	v_cvt_pk_bf16_f32 v152, v145, v146
	v_cvt_pk_bf16_f32 v153, v147, v148
	v_cvt_pk_bf16_f32 v154, v149, v150
	global_store_short v88, v151, s[0:1]
	global_store_short_d16_hi v89, v151, s[0:1]
	global_store_short v90, v152, s[0:1]
	global_store_short_d16_hi v91, v152, s[0:1]
	global_store_short v92, v153, s[0:1]
	global_store_short_d16_hi v93, v153, s[0:1]
	global_store_short v94, v154, s[0:1]
	global_store_short_d16_hi v95, v154, s[0:1]
	v_mul_f32_e32 v131, 0xbfb8aa3b, v48
	v_mul_f32_e32 v132, 0xbfb8aa3b, v49
	v_mul_f32_e32 v133, 0xbfb8aa3b, v50
	v_mul_f32_e32 v134, 0xbfb8aa3b, v51
	v_mul_f32_e32 v135, 0xbfb8aa3b, v52
	v_mul_f32_e32 v136, 0xbfb8aa3b, v53
	v_mul_f32_e32 v137, 0xbfb8aa3b, v54
	v_mul_f32_e32 v138, 0xbfb8aa3b, v55
	v_exp_f32_e32 v131, v131
	v_exp_f32_e32 v132, v132
	v_exp_f32_e32 v133, v133
	v_exp_f32_e32 v134, v134
	v_exp_f32_e32 v135, v135
	v_exp_f32_e32 v136, v136
	v_exp_f32_e32 v137, v137
	v_exp_f32_e32 v138, v138
	v_add_f32_e32 v131, 1.0, v131
	v_add_f32_e32 v132, 1.0, v132
	v_add_f32_e32 v133, 1.0, v133
	v_add_f32_e32 v134, 1.0, v134
	v_add_f32_e32 v135, 1.0, v135
	v_add_f32_e32 v136, 1.0, v136
	v_add_f32_e32 v137, 1.0, v137
	v_add_f32_e32 v138, 1.0, v138
	v_rcp_f32_e32 v131, v131
	v_rcp_f32_e32 v132, v132
	v_rcp_f32_e32 v133, v133
	v_rcp_f32_e32 v134, v134
	v_rcp_f32_e32 v135, v135
	v_rcp_f32_e32 v136, v136
	v_rcp_f32_e32 v137, v137
	v_rcp_f32_e32 v138, v138
	v_mul_f32_e32 v131, v48, v131
	v_mul_f32_e32 v132, v49, v132
	v_mul_f32_e32 v133, v50, v133
	v_mul_f32_e32 v134, v51, v134
	v_mul_f32_e32 v135, v52, v135
	v_mul_f32_e32 v136, v53, v136
	v_mul_f32_e32 v137, v54, v137
	v_mul_f32_e32 v138, v55, v138
	v_mul_f32_e32 v131, v32, v131
	v_mul_f32_e32 v132, v33, v132
	v_mul_f32_e32 v133, v34, v133
	v_mul_f32_e32 v134, v35, v134
	v_mul_f32_e32 v135, v36, v135
	v_mul_f32_e32 v136, v37, v136
	v_mul_f32_e32 v137, v38, v137
	v_mul_f32_e32 v138, v39, v138
	v_add_u32_e32 v48, 64, v128
	v_add_u32_e32 v49, 0x1640, v128
	v_add_u32_e32 v50, 0x2c40, v128
	v_add_u32_e32 v51, 0x4240, v128
	v_add_u32_e32 v52, 0xb040, v128
	v_add_u32_e32 v53, 0xc640, v128
	v_add_u32_e32 v54, 0xdc40, v128
	v_add_u32_e32 v55, 0xf240, v128
	v_cvt_pk_bf16_f32 v139, v131, v132
	v_cvt_pk_bf16_f32 v140, v133, v134
	v_cvt_pk_bf16_f32 v141, v135, v136
	v_cvt_pk_bf16_f32 v142, v137, v138
	global_store_short v48, v139, s[0:1]
	global_store_short_d16_hi v49, v139, s[0:1]
	global_store_short v50, v140, s[0:1]
	global_store_short_d16_hi v51, v140, s[0:1]
	global_store_short v52, v141, s[0:1]
	global_store_short_d16_hi v53, v141, s[0:1]
	global_store_short v54, v142, s[0:1]
	global_store_short_d16_hi v55, v142, s[0:1]
	v_mul_f32_e32 v143, 0xbfb8aa3b, v56
	v_mul_f32_e32 v144, 0xbfb8aa3b, v57
	v_mul_f32_e32 v145, 0xbfb8aa3b, v58
	v_mul_f32_e32 v146, 0xbfb8aa3b, v59
	v_mul_f32_e32 v147, 0xbfb8aa3b, v60
	v_mul_f32_e32 v148, 0xbfb8aa3b, v61
	v_mul_f32_e32 v149, 0xbfb8aa3b, v62
	v_mul_f32_e32 v150, 0xbfb8aa3b, v63
	v_exp_f32_e32 v143, v143
	v_exp_f32_e32 v144, v144
	v_exp_f32_e32 v145, v145
	v_exp_f32_e32 v146, v146
	v_exp_f32_e32 v147, v147
	v_exp_f32_e32 v148, v148
	v_exp_f32_e32 v149, v149
	v_exp_f32_e32 v150, v150
	v_add_f32_e32 v143, 1.0, v143
	v_add_f32_e32 v144, 1.0, v144
	v_add_f32_e32 v145, 1.0, v145
	v_add_f32_e32 v146, 1.0, v146
	v_add_f32_e32 v147, 1.0, v147
	v_add_f32_e32 v148, 1.0, v148
	v_add_f32_e32 v149, 1.0, v149
	v_add_f32_e32 v150, 1.0, v150
	v_rcp_f32_e32 v143, v143
	v_rcp_f32_e32 v144, v144
	v_rcp_f32_e32 v145, v145
	v_rcp_f32_e32 v146, v146
	v_rcp_f32_e32 v147, v147
	v_rcp_f32_e32 v148, v148
	v_rcp_f32_e32 v149, v149
	v_rcp_f32_e32 v150, v150
	v_mul_f32_e32 v143, v56, v143
	v_mul_f32_e32 v144, v57, v144
	v_mul_f32_e32 v145, v58, v145
	v_mul_f32_e32 v146, v59, v146
	v_mul_f32_e32 v147, v60, v147
	v_mul_f32_e32 v148, v61, v148
	v_mul_f32_e32 v149, v62, v149
	v_mul_f32_e32 v150, v63, v150
	v_mul_f32_e32 v143, v40, v143
	v_mul_f32_e32 v144, v41, v144
	v_mul_f32_e32 v145, v42, v145
	v_mul_f32_e32 v146, v43, v146
	v_mul_f32_e32 v147, v44, v147
	v_mul_f32_e32 v148, v45, v148
	v_mul_f32_e32 v149, v46, v149
	v_mul_f32_e32 v150, v47, v150
	v_add_u32_e32 v56, 0x16040, v128
	v_add_u32_e32 v57, 0x17640, v128
	v_add_u32_e32 v58, 0x18c40, v128
	v_add_u32_e32 v59, 0x1a240, v128
	v_add_u32_e32 v60, 0x21040, v128
	v_add_u32_e32 v61, 0x22640, v128
	v_add_u32_e32 v62, 0x23c40, v128
	v_add_u32_e32 v63, 0x25240, v128
	v_cvt_pk_bf16_f32 v151, v143, v144
	v_cvt_pk_bf16_f32 v152, v145, v146
	v_cvt_pk_bf16_f32 v153, v147, v148
	v_cvt_pk_bf16_f32 v154, v149, v150
	global_store_short v56, v151, s[0:1]
	global_store_short_d16_hi v57, v151, s[0:1]
	global_store_short v58, v152, s[0:1]
	global_store_short_d16_hi v59, v152, s[0:1]
	global_store_short v60, v153, s[0:1]
	global_store_short_d16_hi v61, v153, s[0:1]
	global_store_short v62, v154, s[0:1]
	global_store_short_d16_hi v63, v154, s[0:1]
	v_mul_f32_e32 v131, 0xbfb8aa3b, v16
	v_mul_f32_e32 v132, 0xbfb8aa3b, v17
	v_mul_f32_e32 v133, 0xbfb8aa3b, v18
	v_mul_f32_e32 v134, 0xbfb8aa3b, v19
	v_mul_f32_e32 v135, 0xbfb8aa3b, v20
	v_mul_f32_e32 v136, 0xbfb8aa3b, v21
	v_mul_f32_e32 v137, 0xbfb8aa3b, v22
	v_mul_f32_e32 v138, 0xbfb8aa3b, v23
	v_exp_f32_e32 v131, v131
	v_exp_f32_e32 v132, v132
	v_exp_f32_e32 v133, v133
	v_exp_f32_e32 v134, v134
	v_exp_f32_e32 v135, v135
	v_exp_f32_e32 v136, v136
	v_exp_f32_e32 v137, v137
	v_exp_f32_e32 v138, v138
	v_add_f32_e32 v131, 1.0, v131
	v_add_f32_e32 v132, 1.0, v132
	v_add_f32_e32 v133, 1.0, v133
	v_add_f32_e32 v134, 1.0, v134
	v_add_f32_e32 v135, 1.0, v135
	v_add_f32_e32 v136, 1.0, v136
	v_add_f32_e32 v137, 1.0, v137
	v_add_f32_e32 v138, 1.0, v138
	v_rcp_f32_e32 v131, v131
	v_rcp_f32_e32 v132, v132
	v_rcp_f32_e32 v133, v133
	v_rcp_f32_e32 v134, v134
	v_rcp_f32_e32 v135, v135
	v_rcp_f32_e32 v136, v136
	v_rcp_f32_e32 v137, v137
	v_rcp_f32_e32 v138, v138
	v_mul_f32_e32 v131, v16, v131
	v_mul_f32_e32 v132, v17, v132
	v_mul_f32_e32 v133, v18, v133
	v_mul_f32_e32 v134, v19, v134
	v_mul_f32_e32 v135, v20, v135
	v_mul_f32_e32 v136, v21, v136
	v_mul_f32_e32 v137, v22, v137
	v_mul_f32_e32 v138, v23, v138
	v_mul_f32_e32 v131, v0, v131
	v_mul_f32_e32 v132, v1, v132
	v_mul_f32_e32 v133, v2, v133
	v_mul_f32_e32 v134, v3, v134
	v_mul_f32_e32 v135, v4, v135
	v_mul_f32_e32 v136, v5, v136
	v_mul_f32_e32 v137, v6, v137
	v_mul_f32_e32 v138, v7, v138
	v_add_u32_e32 v16, 0x2c040, v128
	v_add_u32_e32 v17, 0x2d640, v128
	v_add_u32_e32 v18, 0x2ec40, v128
	v_add_u32_e32 v19, 0x30240, v128
	v_add_u32_e32 v20, 0x37040, v128
	v_add_u32_e32 v21, 0x38640, v128
	v_add_u32_e32 v22, 0x39c40, v128
	v_add_u32_e32 v23, 0x3b240, v128
	v_cvt_pk_bf16_f32 v139, v131, v132
	v_cvt_pk_bf16_f32 v140, v133, v134
	v_cvt_pk_bf16_f32 v141, v135, v136
	v_cvt_pk_bf16_f32 v142, v137, v138
	global_store_short v16, v139, s[0:1]
	global_store_short_d16_hi v17, v139, s[0:1]
	global_store_short v18, v140, s[0:1]
	global_store_short_d16_hi v19, v140, s[0:1]
	global_store_short v20, v141, s[0:1]
	global_store_short_d16_hi v21, v141, s[0:1]
	global_store_short v22, v142, s[0:1]
	global_store_short_d16_hi v23, v142, s[0:1]
	v_mul_f32_e32 v143, 0xbfb8aa3b, v24
	v_mul_f32_e32 v144, 0xbfb8aa3b, v25
	v_mul_f32_e32 v145, 0xbfb8aa3b, v26
	v_mul_f32_e32 v146, 0xbfb8aa3b, v27
	v_mul_f32_e32 v147, 0xbfb8aa3b, v28
	v_mul_f32_e32 v148, 0xbfb8aa3b, v29
	v_mul_f32_e32 v149, 0xbfb8aa3b, v30
	v_mul_f32_e32 v150, 0xbfb8aa3b, v31
	v_exp_f32_e32 v143, v143
	v_exp_f32_e32 v144, v144
	v_exp_f32_e32 v145, v145
	v_exp_f32_e32 v146, v146
	v_exp_f32_e32 v147, v147
	v_exp_f32_e32 v148, v148
	v_exp_f32_e32 v149, v149
	v_exp_f32_e32 v150, v150
	v_add_f32_e32 v143, 1.0, v143
	v_add_f32_e32 v144, 1.0, v144
	v_add_f32_e32 v145, 1.0, v145
	v_add_f32_e32 v146, 1.0, v146
	v_add_f32_e32 v147, 1.0, v147
	v_add_f32_e32 v148, 1.0, v148
	v_add_f32_e32 v149, 1.0, v149
	v_add_f32_e32 v150, 1.0, v150
	v_rcp_f32_e32 v143, v143
	v_rcp_f32_e32 v144, v144
	v_rcp_f32_e32 v145, v145
	v_rcp_f32_e32 v146, v146
	v_rcp_f32_e32 v147, v147
	v_rcp_f32_e32 v148, v148
	v_rcp_f32_e32 v149, v149
	v_rcp_f32_e32 v150, v150
	v_mul_f32_e32 v143, v24, v143
	v_mul_f32_e32 v144, v25, v144
	v_mul_f32_e32 v145, v26, v145
	v_mul_f32_e32 v146, v27, v146
	v_mul_f32_e32 v147, v28, v147
	v_mul_f32_e32 v148, v29, v148
	v_mul_f32_e32 v149, v30, v149
	v_mul_f32_e32 v150, v31, v150
	v_mul_f32_e32 v143, v8, v143
	v_mul_f32_e32 v144, v9, v144
	v_mul_f32_e32 v145, v10, v145
	v_mul_f32_e32 v146, v11, v146
	v_mul_f32_e32 v147, v12, v147
	v_mul_f32_e32 v148, v13, v148
	v_mul_f32_e32 v149, v14, v149
	v_mul_f32_e32 v150, v15, v150
	v_add_u32_e32 v24, 0x42040, v128
	v_add_u32_e32 v25, 0x43640, v128
	v_add_u32_e32 v26, 0x44c40, v128
	v_add_u32_e32 v27, 0x46240, v128
	v_add_u32_e32 v28, 0x4d040, v128
	v_add_u32_e32 v29, 0x4e640, v128
	v_add_u32_e32 v30, 0x4fc40, v128
	v_add_u32_e32 v31, 0x51240, v128
	v_cvt_pk_bf16_f32 v151, v143, v144
	v_cvt_pk_bf16_f32 v152, v145, v146
	v_cvt_pk_bf16_f32 v153, v147, v148
	v_cvt_pk_bf16_f32 v154, v149, v150
	global_store_short v24, v151, s[0:1]
	global_store_short_d16_hi v25, v151, s[0:1]
	global_store_short v26, v152, s[0:1]
	global_store_short_d16_hi v27, v152, s[0:1]
	global_store_short v28, v153, s[0:1]
	global_store_short_d16_hi v29, v153, s[0:1]
	global_store_short v30, v154, s[0:1]
	global_store_short_d16_hi v31, v154, s[0:1]
	s_add_i32 s12, s12, s85
	s_cmp_ge_i32 s12, s58
	s_cbranch_scc1 .LBB0_1003
